# hyena item epilogue: 16-byte loads/stores with v_permlane32_swap exchanging halves between the two half-waves (was 8-byte accesses at 16-byte stride, twice as many memory instructions over the same li
# speedup vs baseline: 1.0405x; 1.0052x over previous
; #define GAS __attribute__((address_space(1)))
; DI unsigned pk2(float a, float b) { f32x2 v = {a, b}; bf2_t r = __builtin_convertvector(v, bf2_t); return __builtin_bit_cast(unsigned, r); }
; DI float bflo(unsigned w) { return __uint_as_float(w << 16); }
; DI float bfhi(unsigned w) { return __uint_as_float(w & 0xffff0000u); }
; DI f32x16 mfma32(bf16x8 a, bf16x8 b, f32x16 c) { return __builtin_amdgcn_mfma_f32_32x32x16_bf16(a, b, c, 0, 0, 0); }
; DI void hyena_item(char* smem, const bf16_t* __restrict__ zin, const bf16_t* __restrict__ xg, const bf16_t* __restrict__ arr, float bias, bf16_t* __restrict__ zout, int tq, int tid) {
;     ...
;     for (int sc = 0; sc < 16; ++sc) {
;       const bf16x8 zf = *(const bf16x8*)(zs + r * ZSB + sc * 32 + h * 16);
;       const char* gp = gbase + (pnl * 256 + sc * 16) * 2;
; #pragma unroll
;       for (int i = 0; i < 4; ++i) {
;         const s16x4 g0 = *(const s16x4*)(gp - 64 * i), g1 = *(const s16x4*)(gp - 64 * i + 8);
;         const bf16x8 gf = __builtin_shufflevector(g0, g1, 0, 1, 2, 3, 4, 5, 6, 7);
;         acc[i] = mfma32(gf, zf, acc[i]);
;       }
;     }
;     if (more) {
;       char* zn = smem + ZOFF + ((pnl + 1) & 1) * ZPB;
; #pragma unroll
;       for (int i = 0; i < 4; ++i) *(u32x4*)(zn + (zb + 8 * i) * ZSB + zc * 16) = zr[i];
;     }
;     __syncthreads();
;   }
; #pragma unroll
;   for (int i = 0; i < 4; ++i) {
;     const int t0 = 512 * tq + 128 * wid + 32 * i;
; #pragma unroll
;     for (int g = 0; g < 4; ++g) {
;       const size_t off = (size_t)r * 2048 + t0 + 8 * g + 4 * h;
;       const u32x2 zw = *(const GAS u32x2*)(zin + off), xw = *(const GAS u32x2*)(xg + off);
;       const float o0 = bflo(xw.x) * (acc[i][4 * g + 0] + bias * bflo(zw.x));
;       const float o1 = bfhi(xw.x) * (acc[i][4 * g + 1] + bias * bfhi(zw.x));
;       const float o2 = bflo(xw.y) * (acc[i][4 * g + 2] + bias * bflo(zw.y));
;       const float o3 = bfhi(xw.y) * (acc[i][4 * g + 3] + bias * bfhi(zw.y));
;       u32x2 w; w.x = pk2(o0, o1); w.y = pk2(o2, o3);
;       *(GAS u32x2*)(zout + off) = w;
;     }
;   }
.LBB0_338:
	v_add_u32_e32 v96, s13, v156
	v_add_u32_e32 v83, s13, v150
	ds_read2_b64 v[66:69], v96 offset0:24 offset1:25
	ds_read_b128 v[70:73], v83
	ds_read_b128 v[74:77], v83 offset:32
	ds_read2_b64 v[78:81], v96 offset0:16 offset1:17
	ds_read2_b64 v[84:87], v96 offset0:8 offset1:9
	ds_read2_b64 v[88:91], v96 offset1:1
	s_waitcnt lgkmcnt(4)
	v_mfma_f32_32x32x16_bf16 v[50:65], v[66:69], v[70:73], v[50:65]
	ds_read2_b64 v[92:95], v96 offset0:12 offset1:13
	ds_read2_b64 v[160:163], v96 offset0:4 offset1:5
	s_addk_i32 s13, 0x80
	s_cmpk_lg_i32 s13, 0x200
	s_waitcnt lgkmcnt(4)
	v_mfma_f32_32x32x16_bf16 v[34:49], v[78:81], v[70:73], v[34:49]
	s_waitcnt lgkmcnt(3)
	v_mfma_f32_32x32x16_bf16 v[18:33], v[84:87], v[70:73], v[18:33]
	s_waitcnt lgkmcnt(2)
	v_mfma_f32_32x32x16_bf16 v[2:17], v[88:91], v[70:73], v[2:17]
	ds_read2_b64 v[70:73], v96 offset0:28 offset1:29
	ds_read2_b64 v[88:91], v96 offset0:20 offset1:21
	s_waitcnt lgkmcnt(1)
	v_mfma_f32_32x32x16_bf16 v[50:65], v[70:73], v[74:77], v[50:65]
	s_waitcnt lgkmcnt(0)
	v_mfma_f32_32x32x16_bf16 v[34:49], v[88:91], v[74:77], v[34:49]
	v_mfma_f32_32x32x16_bf16 v[18:33], v[92:95], v[74:77], v[18:33]
	v_mfma_f32_32x32x16_bf16 v[2:17], v[160:163], v[74:77], v[2:17]
	ds_read_b128 v[74:77], v83 offset:64
	ds_read2_b64 v[160:163], v96 offset0:32 offset1:33
	s_waitcnt lgkmcnt(0)
	v_mfma_f32_32x32x16_bf16 v[50:65], v[160:163], v[74:77], v[50:65]
	v_mfma_f32_32x32x16_bf16 v[34:49], v[66:69], v[74:77], v[34:49]
	v_mfma_f32_32x32x16_bf16 v[18:33], v[78:81], v[74:77], v[18:33]
	v_mfma_f32_32x32x16_bf16 v[2:17], v[84:87], v[74:77], v[2:17]
	ds_read_b128 v[66:69], v83 offset:96
	ds_read2_b64 v[74:77], v96 offset0:36 offset1:37
	s_waitcnt lgkmcnt(0)
	v_mfma_f32_32x32x16_bf16 v[50:65], v[74:77], v[66:69], v[50:65]
	v_mfma_f32_32x32x16_bf16 v[34:49], v[70:73], v[66:69], v[34:49]
	v_mfma_f32_32x32x16_bf16 v[18:33], v[88:91], v[66:69], v[18:33]
	v_mfma_f32_32x32x16_bf16 v[2:17], v[92:95], v[66:69], v[2:17]
	s_cbranch_scc1 .LBB0_338
	s_add_i32 s10, s53, s12
	v_add_u32_e32 v66, s62, v143
	s_ashr_i32 s11, s10, 31
	v_ashrrev_i32_e32 v67, 31, v66
	s_lshl_b64 s[10:11], s[10:11], 17
	v_lshl_add_u64 v[66:67], v[66:67], 0, v[116:117]
	s_add_u32 s10, s47, s10
	v_lshlrev_b64 v[70:71], 1, v[66:67]
	s_addc_u32 s11, s52, s11
	v_lshl_add_u64 v[68:69], s[14:15], 0, v[70:71]
	s_barrier
	v_lshl_add_u64 v[66:67], s[10:11], 0, v[70:71]
	s_add_u32 s12, s59, s16
	s_addc_u32 s13, s60, s17
	s_mov_b64 s[10:11], 0xf0
	v_lshl_add_u64 v[84:85], s[12:13], 0, v[70:71]
	v_mbcnt_lo_u32_b32 v72, -1, 0
	v_mbcnt_hi_u32_b32 v72, -1, v72
	v_and_b32_e32 v72, 32, v72
	v_lshrrev_b32_e32 v72, 2, v72
	v_mov_b32_e32 v73, 0
	v_lshl_add_u64 v[68:69], v[68:69], 0, v[72:73]
	v_lshl_add_u64 v[66:67], v[66:67], 0, v[72:73]
	v_lshl_add_u64 v[86:87], v[84:85], 0, v[72:73]
	global_load_dwordx4 v[226:229], v[68:69], off
	global_load_dwordx4 v[230:233], v[66:67], off
	global_load_dwordx4 v[234:237], v[68:69], off offset:32
	global_load_dwordx4 v[238:241], v[66:67], off offset:32
	global_load_dwordx4 v[242:245], v[68:69], off offset:64
	global_load_dwordx4 v[246:249], v[66:67], off offset:64
	global_load_dwordx4 v[160:163], v[68:69], off offset:96
	global_load_dwordx4 v[88:91], v[66:67], off offset:96
	s_waitcnt vmcnt(6)
	v_permlane32_swap_b32_e32 v226, v228
	v_permlane32_swap_b32_e32 v227, v229
	v_permlane32_swap_b32_e32 v230, v232
	v_permlane32_swap_b32_e32 v231, v233
	v_lshlrev_b32_e32 v72, 16, v226
	v_and_b32_e32 v73, 0xffff0000, v226
	v_lshlrev_b32_e32 v74, 16, v227
	v_and_b32_e32 v75, 0xffff0000, v227
	v_lshlrev_b32_e32 v76, 16, v230
	v_and_b32_e32 v77, 0xffff0000, v230
	v_lshlrev_b32_e32 v78, 16, v231
	v_and_b32_e32 v79, 0xffff0000, v231
	v_fma_f32 v50, v82, v72, v50
	v_fma_f32 v51, v82, v73, v51
	v_fma_f32 v52, v82, v74, v52
	v_fma_f32 v53, v82, v75, v53
	v_mul_f32_e32 v50, v50, v76
	v_mul_f32_e32 v51, v51, v77
	v_mul_f32_e32 v52, v52, v78
	v_mul_f32_e32 v53, v53, v79
	v_cvt_pk_bf16_f32 v92, v50, v51
	v_cvt_pk_bf16_f32 v93, v52, v53
	v_lshlrev_b32_e32 v72, 16, v228
	v_and_b32_e32 v73, 0xffff0000, v228
	v_lshlrev_b32_e32 v74, 16, v229
	v_and_b32_e32 v75, 0xffff0000, v229
	v_lshlrev_b32_e32 v76, 16, v232
	v_and_b32_e32 v77, 0xffff0000, v232
	v_lshlrev_b32_e32 v78, 16, v233
	v_and_b32_e32 v79, 0xffff0000, v233
	v_fma_f32 v54, v82, v72, v54
	v_fma_f32 v55, v82, v73, v55
	v_fma_f32 v56, v82, v74, v56
	v_fma_f32 v57, v82, v75, v57
	v_mul_f32_e32 v54, v54, v76
	v_mul_f32_e32 v55, v55, v77
	v_mul_f32_e32 v56, v56, v78
	v_mul_f32_e32 v57, v57, v79
	v_cvt_pk_bf16_f32 v94, v54, v55
	v_cvt_pk_bf16_f32 v95, v56, v57
	s_nop 1
	v_permlane32_swap_b32_e32 v92, v94
	v_permlane32_swap_b32_e32 v93, v95
	global_store_dwordx4 v[86:87], v[92:95], off
	s_waitcnt vmcnt(5)
	v_permlane32_swap_b32_e32 v234, v236
	v_permlane32_swap_b32_e32 v235, v237
	v_permlane32_swap_b32_e32 v238, v240
	v_permlane32_swap_b32_e32 v239, v241
	v_lshlrev_b32_e32 v72, 16, v234
	v_and_b32_e32 v73, 0xffff0000, v234
	v_lshlrev_b32_e32 v74, 16, v235
	v_and_b32_e32 v75, 0xffff0000, v235
	v_lshlrev_b32_e32 v76, 16, v238
	v_and_b32_e32 v77, 0xffff0000, v238
	v_lshlrev_b32_e32 v78, 16, v239
	v_and_b32_e32 v79, 0xffff0000, v239
	v_fma_f32 v58, v82, v72, v58
	v_fma_f32 v59, v82, v73, v59
	v_fma_f32 v60, v82, v74, v60
	v_fma_f32 v61, v82, v75, v61
	v_mul_f32_e32 v58, v58, v76
	v_mul_f32_e32 v59, v59, v77
	v_mul_f32_e32 v60, v60, v78
	v_mul_f32_e32 v61, v61, v79
	v_cvt_pk_bf16_f32 v92, v58, v59
	v_cvt_pk_bf16_f32 v93, v60, v61
	v_lshlrev_b32_e32 v72, 16, v236
	v_and_b32_e32 v73, 0xffff0000, v236
	v_lshlrev_b32_e32 v74, 16, v237
	v_and_b32_e32 v75, 0xffff0000, v237
	v_lshlrev_b32_e32 v76, 16, v240
	v_and_b32_e32 v77, 0xffff0000, v240
	v_lshlrev_b32_e32 v78, 16, v241
	v_and_b32_e32 v79, 0xffff0000, v241
	v_fma_f32 v62, v82, v72, v62
	v_fma_f32 v63, v82, v73, v63
	v_fma_f32 v64, v82, v74, v64
	v_fma_f32 v65, v82, v75, v65
	v_mul_f32_e32 v62, v62, v76
	v_mul_f32_e32 v63, v63, v77
	v_mul_f32_e32 v64, v64, v78
	v_mul_f32_e32 v65, v65, v79
	v_cvt_pk_bf16_f32 v94, v62, v63
	v_cvt_pk_bf16_f32 v95, v64, v65
	s_nop 1
	v_permlane32_swap_b32_e32 v92, v94
	v_permlane32_swap_b32_e32 v93, v95
	global_store_dwordx4 v[86:87], v[92:95], off offset:32
	s_waitcnt vmcnt(4)
; #define GAS __attribute__((address_space(1)))
; DI unsigned pk2(float a, float b) { f32x2 v = {a, b}; bf2_t r = __builtin_convertvector(v, bf2_t); return __builtin_bit_cast(unsigned, r); }
; DI float bflo(unsigned w) { return __uint_as_float(w << 16); }
; DI float bfhi(unsigned w) { return __uint_as_float(w & 0xffff0000u); }
; DI void hyena_item(char* smem, const bf16_t* __restrict__ zin, const bf16_t* __restrict__ xg, const bf16_t* __restrict__ arr, float bias, bf16_t* __restrict__ zout, int tq, int tid) {
;     ...
; #pragma unroll
;   for (int i = 0; i < 4; ++i) {
;     const int t0 = 512 * tq + 128 * wid + 32 * i;
; #pragma unroll
;     for (int g = 0; g < 4; ++g) {
;       const size_t off = (size_t)r * 2048 + t0 + 8 * g + 4 * h;
;       const u32x2 zw = *(const GAS u32x2*)(zin + off), xw = *(const GAS u32x2*)(xg + off);
;       const float o0 = bflo(xw.x) * (acc[i][4 * g + 0] + bias * bflo(zw.x));
;       const float o1 = bfhi(xw.x) * (acc[i][4 * g + 1] + bias * bfhi(zw.x));
;       const float o2 = bflo(xw.y) * (acc[i][4 * g + 2] + bias * bflo(zw.y));
;       const float o3 = bfhi(xw.y) * (acc[i][4 * g + 3] + bias * bfhi(zw.y));
;       u32x2 w; w.x = pk2(o0, o1); w.y = pk2(o2, o3);
;       *(GAS u32x2*)(zout + off) = w;
;     }
;   }
	v_permlane32_swap_b32_e32 v242, v244
	v_permlane32_swap_b32_e32 v243, v245
	v_permlane32_swap_b32_e32 v246, v248
	v_permlane32_swap_b32_e32 v247, v249
	v_lshlrev_b32_e32 v72, 16, v242
	v_and_b32_e32 v73, 0xffff0000, v242
	v_lshlrev_b32_e32 v74, 16, v243
	v_and_b32_e32 v75, 0xffff0000, v243
	v_lshlrev_b32_e32 v76, 16, v246
	v_and_b32_e32 v77, 0xffff0000, v246
	v_lshlrev_b32_e32 v78, 16, v247
	v_and_b32_e32 v79, 0xffff0000, v247
	v_fma_f32 v34, v82, v72, v34
	v_fma_f32 v35, v82, v73, v35
	v_fma_f32 v36, v82, v74, v36
	v_fma_f32 v37, v82, v75, v37
	v_mul_f32_e32 v34, v34, v76
	v_mul_f32_e32 v35, v35, v77
	v_mul_f32_e32 v36, v36, v78
	v_mul_f32_e32 v37, v37, v79
	v_cvt_pk_bf16_f32 v92, v34, v35
	v_cvt_pk_bf16_f32 v93, v36, v37
	v_lshlrev_b32_e32 v72, 16, v244
	v_and_b32_e32 v73, 0xffff0000, v244
	v_lshlrev_b32_e32 v74, 16, v245
	v_and_b32_e32 v75, 0xffff0000, v245
	v_lshlrev_b32_e32 v76, 16, v248
	v_and_b32_e32 v77, 0xffff0000, v248
	v_lshlrev_b32_e32 v78, 16, v249
	v_and_b32_e32 v79, 0xffff0000, v249
	v_fma_f32 v38, v82, v72, v38
	v_fma_f32 v39, v82, v73, v39
	v_fma_f32 v40, v82, v74, v40
	v_fma_f32 v41, v82, v75, v41
	v_mul_f32_e32 v38, v38, v76
	v_mul_f32_e32 v39, v39, v77
	v_mul_f32_e32 v40, v40, v78
	v_mul_f32_e32 v41, v41, v79
	v_cvt_pk_bf16_f32 v94, v38, v39
	v_cvt_pk_bf16_f32 v95, v40, v41
	s_nop 1
	v_permlane32_swap_b32_e32 v92, v94
	v_permlane32_swap_b32_e32 v93, v95
	global_store_dwordx4 v[86:87], v[92:95], off offset:64
	s_waitcnt vmcnt(3)
	v_permlane32_swap_b32_e32 v160, v162
	v_permlane32_swap_b32_e32 v161, v163
	v_permlane32_swap_b32_e32 v88, v90
	v_permlane32_swap_b32_e32 v89, v91
	v_lshlrev_b32_e32 v72, 16, v160
	v_and_b32_e32 v73, 0xffff0000, v160
	v_lshlrev_b32_e32 v74, 16, v161
	v_and_b32_e32 v75, 0xffff0000, v161
	v_lshlrev_b32_e32 v76, 16, v88
	v_and_b32_e32 v77, 0xffff0000, v88
	v_lshlrev_b32_e32 v78, 16, v89
	v_and_b32_e32 v79, 0xffff0000, v89
	v_fma_f32 v42, v82, v72, v42
	v_fma_f32 v43, v82, v73, v43
	v_fma_f32 v44, v82, v74, v44
	v_fma_f32 v45, v82, v75, v45
	v_mul_f32_e32 v42, v42, v76
	v_mul_f32_e32 v43, v43, v77
	v_mul_f32_e32 v44, v44, v78
	v_mul_f32_e32 v45, v45, v79
	v_cvt_pk_bf16_f32 v92, v42, v43
	v_cvt_pk_bf16_f32 v93, v44, v45
	v_lshlrev_b32_e32 v72, 16, v162
	v_and_b32_e32 v73, 0xffff0000, v162
	v_lshlrev_b32_e32 v74, 16, v163
	v_and_b32_e32 v75, 0xffff0000, v163
	v_lshlrev_b32_e32 v76, 16, v90
	v_and_b32_e32 v77, 0xffff0000, v90
	v_lshlrev_b32_e32 v78, 16, v91
	v_and_b32_e32 v79, 0xffff0000, v91
	v_fma_f32 v46, v82, v72, v46
	v_fma_f32 v47, v82, v73, v47
	v_fma_f32 v48, v82, v74, v48
	v_fma_f32 v49, v82, v75, v49
	v_mul_f32_e32 v46, v46, v76
	v_mul_f32_e32 v47, v47, v77
	v_mul_f32_e32 v48, v48, v78
	v_mul_f32_e32 v49, v49, v79
	v_cvt_pk_bf16_f32 v94, v46, v47
	v_cvt_pk_bf16_f32 v95, v48, v49
	s_nop 1
	v_permlane32_swap_b32_e32 v92, v94
	v_permlane32_swap_b32_e32 v93, v95
	global_store_dwordx4 v[86:87], v[92:95], off offset:96
	global_load_dwordx4 v[226:229], v[68:69], off offset:128
	global_load_dwordx4 v[230:233], v[66:67], off offset:128
	global_load_dwordx4 v[234:237], v[68:69], off offset:160
	global_load_dwordx4 v[238:241], v[66:67], off offset:160
	global_load_dwordx4 v[242:245], v[68:69], off offset:192
	global_load_dwordx4 v[246:249], v[66:67], off offset:192
	global_load_dwordx4 v[160:163], v[68:69], off offset:224
	global_load_dwordx4 v[88:91], v[66:67], off offset:224
	s_waitcnt vmcnt(6)
	v_permlane32_swap_b32_e32 v226, v228
	v_permlane32_swap_b32_e32 v227, v229
	v_permlane32_swap_b32_e32 v230, v232
	v_permlane32_swap_b32_e32 v231, v233
	v_lshlrev_b32_e32 v72, 16, v226
	v_and_b32_e32 v73, 0xffff0000, v226
	v_lshlrev_b32_e32 v74, 16, v227
	v_and_b32_e32 v75, 0xffff0000, v227
	v_lshlrev_b32_e32 v76, 16, v230
	v_and_b32_e32 v77, 0xffff0000, v230
	v_lshlrev_b32_e32 v78, 16, v231
	v_and_b32_e32 v79, 0xffff0000, v231
	v_fma_f32 v18, v82, v72, v18
	v_fma_f32 v19, v82, v73, v19
	v_fma_f32 v20, v82, v74, v20
	v_fma_f32 v21, v82, v75, v21
	v_mul_f32_e32 v18, v18, v76
	v_mul_f32_e32 v19, v19, v77
	v_mul_f32_e32 v20, v20, v78
	v_mul_f32_e32 v21, v21, v79
	v_cvt_pk_bf16_f32 v92, v18, v19
	v_cvt_pk_bf16_f32 v93, v20, v21
	v_lshlrev_b32_e32 v72, 16, v228
	v_and_b32_e32 v73, 0xffff0000, v228
	v_lshlrev_b32_e32 v74, 16, v229
	v_and_b32_e32 v75, 0xffff0000, v229
	v_lshlrev_b32_e32 v76, 16, v232
	v_and_b32_e32 v77, 0xffff0000, v232
	v_lshlrev_b32_e32 v78, 16, v233
	v_and_b32_e32 v79, 0xffff0000, v233
	v_fma_f32 v22, v82, v72, v22
	v_fma_f32 v23, v82, v73, v23
	v_fma_f32 v24, v82, v74, v24
	v_fma_f32 v25, v82, v75, v25
	v_mul_f32_e32 v22, v22, v76
	v_mul_f32_e32 v23, v23, v77
	v_mul_f32_e32 v24, v24, v78
	v_mul_f32_e32 v25, v25, v79
	v_cvt_pk_bf16_f32 v94, v22, v23
	v_cvt_pk_bf16_f32 v95, v24, v25
	s_nop 1
	v_permlane32_swap_b32_e32 v92, v94
	v_permlane32_swap_b32_e32 v93, v95
	global_store_dwordx4 v[86:87], v[92:95], off offset:128
	s_waitcnt vmcnt(5)
; #define GAS __attribute__((address_space(1)))
; DI unsigned pk2(float a, float b) { f32x2 v = {a, b}; bf2_t r = __builtin_convertvector(v, bf2_t); return __builtin_bit_cast(unsigned, r); }
; DI float bflo(unsigned w) { return __uint_as_float(w << 16); }
; DI float bfhi(unsigned w) { return __uint_as_float(w & 0xffff0000u); }
; DI void hyena_item(char* smem, const bf16_t* __restrict__ zin, const bf16_t* __restrict__ xg, const bf16_t* __restrict__ arr, float bias, bf16_t* __restrict__ zout, int tq, int tid) {
;     ...
; #pragma unroll
;   for (int i = 0; i < 4; ++i) {
;     const int t0 = 512 * tq + 128 * wid + 32 * i;
; #pragma unroll
;     for (int g = 0; g < 4; ++g) {
;       const size_t off = (size_t)r * 2048 + t0 + 8 * g + 4 * h;
;       const u32x2 zw = *(const GAS u32x2*)(zin + off), xw = *(const GAS u32x2*)(xg + off);
;       const float o0 = bflo(xw.x) * (acc[i][4 * g + 0] + bias * bflo(zw.x));
;       const float o1 = bfhi(xw.x) * (acc[i][4 * g + 1] + bias * bfhi(zw.x));
;       const float o2 = bflo(xw.y) * (acc[i][4 * g + 2] + bias * bflo(zw.y));
;       const float o3 = bfhi(xw.y) * (acc[i][4 * g + 3] + bias * bfhi(zw.y));
;       u32x2 w; w.x = pk2(o0, o1); w.y = pk2(o2, o3);
;       *(GAS u32x2*)(zout + off) = w;
;     }
;   }
	v_permlane32_swap_b32_e32 v234, v236
	v_permlane32_swap_b32_e32 v235, v237
	v_permlane32_swap_b32_e32 v238, v240
	v_permlane32_swap_b32_e32 v239, v241
	v_lshlrev_b32_e32 v72, 16, v234
	v_and_b32_e32 v73, 0xffff0000, v234
	v_lshlrev_b32_e32 v74, 16, v235
	v_and_b32_e32 v75, 0xffff0000, v235
	v_lshlrev_b32_e32 v76, 16, v238
	v_and_b32_e32 v77, 0xffff0000, v238
	v_lshlrev_b32_e32 v78, 16, v239
	v_and_b32_e32 v79, 0xffff0000, v239
	v_fma_f32 v26, v82, v72, v26
	v_fma_f32 v27, v82, v73, v27
	v_fma_f32 v28, v82, v74, v28
	v_fma_f32 v29, v82, v75, v29
	v_mul_f32_e32 v26, v26, v76
	v_mul_f32_e32 v27, v27, v77
	v_mul_f32_e32 v28, v28, v78
	v_mul_f32_e32 v29, v29, v79
	v_cvt_pk_bf16_f32 v92, v26, v27
	v_cvt_pk_bf16_f32 v93, v28, v29
	v_lshlrev_b32_e32 v72, 16, v236
	v_and_b32_e32 v73, 0xffff0000, v236
	v_lshlrev_b32_e32 v74, 16, v237
	v_and_b32_e32 v75, 0xffff0000, v237
	v_lshlrev_b32_e32 v76, 16, v240
	v_and_b32_e32 v77, 0xffff0000, v240
	v_lshlrev_b32_e32 v78, 16, v241
	v_and_b32_e32 v79, 0xffff0000, v241
	v_fma_f32 v30, v82, v72, v30
	v_fma_f32 v31, v82, v73, v31
	v_fma_f32 v32, v82, v74, v32
	v_fma_f32 v33, v82, v75, v33
	v_mul_f32_e32 v30, v30, v76
	v_mul_f32_e32 v31, v31, v77
	v_mul_f32_e32 v32, v32, v78
	v_mul_f32_e32 v33, v33, v79
	v_cvt_pk_bf16_f32 v94, v30, v31
	v_cvt_pk_bf16_f32 v95, v32, v33
	s_nop 1
	v_permlane32_swap_b32_e32 v92, v94
	v_permlane32_swap_b32_e32 v93, v95
	global_store_dwordx4 v[86:87], v[92:95], off offset:160
	s_waitcnt vmcnt(4)
	v_permlane32_swap_b32_e32 v242, v244
	v_permlane32_swap_b32_e32 v243, v245
	v_permlane32_swap_b32_e32 v246, v248
	v_permlane32_swap_b32_e32 v247, v249
	v_lshlrev_b32_e32 v72, 16, v242
	v_and_b32_e32 v73, 0xffff0000, v242
	v_lshlrev_b32_e32 v74, 16, v243
	v_and_b32_e32 v75, 0xffff0000, v243
	v_lshlrev_b32_e32 v76, 16, v246
	v_and_b32_e32 v77, 0xffff0000, v246
	v_lshlrev_b32_e32 v78, 16, v247
	v_and_b32_e32 v79, 0xffff0000, v247
	v_fma_f32 v2, v82, v72, v2
	v_fma_f32 v3, v82, v73, v3
	v_fma_f32 v4, v82, v74, v4
	v_fma_f32 v5, v82, v75, v5
	v_mul_f32_e32 v2, v2, v76
	v_mul_f32_e32 v3, v3, v77
	v_mul_f32_e32 v4, v4, v78
	v_mul_f32_e32 v5, v5, v79
	v_cvt_pk_bf16_f32 v92, v2, v3
	v_cvt_pk_bf16_f32 v93, v4, v5
	v_lshlrev_b32_e32 v72, 16, v244
	v_and_b32_e32 v73, 0xffff0000, v244
	v_lshlrev_b32_e32 v74, 16, v245
	v_and_b32_e32 v75, 0xffff0000, v245
	v_lshlrev_b32_e32 v76, 16, v248
	v_and_b32_e32 v77, 0xffff0000, v248
	v_lshlrev_b32_e32 v78, 16, v249
	v_and_b32_e32 v79, 0xffff0000, v249
	v_fma_f32 v6, v82, v72, v6
	v_fma_f32 v7, v82, v73, v7
	v_fma_f32 v8, v82, v74, v8
	v_fma_f32 v9, v82, v75, v9
	v_mul_f32_e32 v6, v6, v76
	v_mul_f32_e32 v7, v7, v77
	v_mul_f32_e32 v8, v8, v78
	v_mul_f32_e32 v9, v9, v79
	v_cvt_pk_bf16_f32 v94, v6, v7
	v_cvt_pk_bf16_f32 v95, v8, v9
	s_nop 1
	v_permlane32_swap_b32_e32 v92, v94
	v_permlane32_swap_b32_e32 v93, v95
	global_store_dwordx4 v[86:87], v[92:95], off offset:192
	s_waitcnt vmcnt(3)
	v_permlane32_swap_b32_e32 v160, v162
	v_permlane32_swap_b32_e32 v161, v163
	v_permlane32_swap_b32_e32 v88, v90
	v_permlane32_swap_b32_e32 v89, v91
	v_lshlrev_b32_e32 v72, 16, v160
	v_and_b32_e32 v73, 0xffff0000, v160
	v_lshlrev_b32_e32 v74, 16, v161
	v_and_b32_e32 v75, 0xffff0000, v161
	v_lshlrev_b32_e32 v76, 16, v88
	v_and_b32_e32 v77, 0xffff0000, v88
	v_lshlrev_b32_e32 v78, 16, v89
	v_and_b32_e32 v79, 0xffff0000, v89
	v_fma_f32 v10, v82, v72, v10
	v_fma_f32 v11, v82, v73, v11
	v_fma_f32 v12, v82, v74, v12
	v_fma_f32 v13, v82, v75, v13
	v_mul_f32_e32 v10, v10, v76
	v_mul_f32_e32 v11, v11, v77
	v_mul_f32_e32 v12, v12, v78
	v_mul_f32_e32 v13, v13, v79
	v_cvt_pk_bf16_f32 v92, v10, v11
	v_cvt_pk_bf16_f32 v93, v12, v13
	v_lshlrev_b32_e32 v72, 16, v162
	v_and_b32_e32 v73, 0xffff0000, v162
	v_lshlrev_b32_e32 v74, 16, v163
	v_and_b32_e32 v75, 0xffff0000, v163
	v_lshlrev_b32_e32 v76, 16, v90
	v_and_b32_e32 v77, 0xffff0000, v90
	v_lshlrev_b32_e32 v78, 16, v91
	v_and_b32_e32 v79, 0xffff0000, v91
	v_fma_f32 v14, v82, v72, v14
	v_fma_f32 v15, v82, v73, v15
	v_fma_f32 v16, v82, v74, v16
	v_fma_f32 v17, v82, v75, v17
	v_mul_f32_e32 v14, v14, v76
	v_mul_f32_e32 v15, v15, v77
	v_mul_f32_e32 v16, v16, v78
	v_mul_f32_e32 v17, v17, v79
	v_cvt_pk_bf16_f32 v94, v14, v15
	v_cvt_pk_bf16_f32 v95, v16, v17
	v_mov_b32_e32 v2, v94
	v_mov_b32_e32 v3, v95
	s_nop 1
	v_permlane32_swap_b32_e32 v92, v94
	v_permlane32_swap_b32_e32 v93, v95
	global_store_dwordx4 v[86:87], v[92:95], off offset:224
	v_lshl_add_u64 v[4:5], v[84:85], 0, s[10:11]
	s_branch .LBB0_301
